# branch-GEMM epilogue: second-row-half gate lines touched (one dword load per wave, a line per lane) together with the first half's loads
# baseline (speedup 1.0000x reference)
; __device__ __forceinline__ unsigned cvtpk(float lo, float hi) { unsigned r; asm volatile("v_cvt_pk_bf16_f32 %0, %1, %2" : "=v"(r) : "v"(lo), "v"(hi)); return r; }
;     __device__ __forceinline__ void operator()(f32x4 (&acc)[2][2][4][2], const pg8::Unit& u, int wr, int wc, int fr, int fq) const {
;     ...
;         for (int ai = 0; ai < 2; ++ai) {
;             u32x2 ga[4][2], gb[4][2];
; #pragma unroll
;             for (int m = 0; m < 4; ++m) {
;                 const unsigned char* gp = gq + (size_t)(row0 + ai * 128 + m * 16) * 4096 + u.pn * 256 + cin;
; #pragma unroll
;                 for (int bj = 0; bj < 2; ++bj) { ga[m][bj] = *(const u32x2*)(gp + bj * 128);
;                     gb[m][bj] = last ? (u32x2){0x01010101u, 0x01010101u} : *(const u32x2*)(gp + 1024 + bj * 128); }
;             }
; #pragma unroll
;             for (int m = 0; m < 4; ++m) {
;                 u16* op = hbuf + (size_t)(row0 + ai * 128 + m * 16) * DM + (u.pn & 3) * 256 + cin;
; #pragma unroll
;                 for (int bj = 0; bj < 2; ++bj) {
;                     f32x4 vv[2];
; #pragma unroll
;                     for (int n = 0; n < 2; ++n) {
;                         const unsigned a4 = ga[m][bj][n], b4 = gb[m][bj][n]; f32x4 v = acc[ai][bj][m][n];
; #pragma unroll
;                         for (int j = 0; j < 4; ++j) { const float ga_ = fmaxf((float)((a4 >> (8 * j)) & 255u), 1.f), gb_ = fmaxf((float)((b4 >> (8 * j)) & 255u), 1.f);
;                             v[j] *= last ? ga_ * (1.f / 255.f) : ga_ * __builtin_amdgcn_rcpf(gb_); }
;                         vv[n] = v; if (!last) acc[ai][bj][m][n] = v;
;                     }
;                     if (last) { u32x4 o = {cvtpk(vv[0][0], vv[0][1]), cvtpk(vv[0][2], vv[0][3]), cvtpk(vv[1][0], vv[1][1]), cvtpk(vv[1][2], vv[1][3])}; *(u32x4*)(op + bj * 128) = o; }
;                 }
.LBB0_40:
	v_bfe_u32 v216, v198, 2, 7
	v_sub_u32_e32 v217, v144, v163
	v_add_u32_e32 v216, v216, v217
	v_add_u32_e32 v216, 0x80, v216
	v_lshlrev_b32_e32 v216, 12, v216
	v_and_b32_e32 v217, 1, v198
	v_lshl_add_u32 v216, v217, 7, v216
	v_and_b32_e32 v217, 2, v198
	v_lshlrev_b32_e32 v217, 9, v217
	v_cndmask_b32_e64 v217, v217, 0, s[38:39]
	v_add_u32_e32 v216, v216, v217
	v_mov_b32_e32 v217, 0
	v_lshl_add_u64 v[214:215], v[146:147], 0, v[216:217]
	global_load_dword v213, v[214:215], off
	v_lshlrev_b64 v[194:195], 11, v[144:145]
	s_waitcnt vmcnt(0)
	v_cvt_f32_ubyte0_e32 v145, v196
	v_rcp_f32_e32 v145, v145
	v_cvt_f32_ubyte0_e32 v213, v192
	v_cvt_f32_ubyte1_e32 v216, v193
	v_cndmask_b32_e64 v145, v145, v203, s[38:39]
	v_mul_f32_e32 v145, v213, v145
	v_cvt_f32_ubyte1_e32 v213, v196
	v_rcp_f32_e32 v214, v213
	v_mul_f32_e32 v213, v126, v145
	v_cvt_f32_ubyte1_e32 v145, v192
	v_cndmask_b32_e64 v214, v214, v203, s[38:39]
	v_mul_f32_e32 v145, v145, v214
	v_cvt_f32_ubyte2_e32 v214, v196
	v_rcp_f32_e32 v215, v214
	v_mul_f32_e32 v214, v127, v145
	v_cvt_f32_ubyte2_e32 v145, v192
	v_cvt_f32_ubyte3_e32 v196, v196
	v_cndmask_b32_e64 v215, v215, v203, s[38:39]
	v_mul_f32_e32 v145, v145, v215
	v_rcp_f32_e32 v215, v196
	v_mul_f32_e32 v196, v128, v145
	v_cvt_f32_ubyte3_e32 v145, v192
	v_cndmask_b32_e64 v192, v215, v203, s[38:39]
	v_mul_f32_e32 v145, v145, v192
	v_cvt_f32_ubyte0_e32 v192, v197
	v_rcp_f32_e32 v192, v192
	v_mul_f32_e32 v215, v129, v145
	v_cvt_f32_ubyte0_e32 v145, v193
	v_cndmask_b32_e64 v192, v192, v203, s[38:39]
	v_mul_f32_e32 v145, v145, v192
	v_cvt_f32_ubyte1_e32 v192, v197
	v_rcp_f32_e32 v192, v192
	v_cvt_f32_ubyte2_e32 v217, v193
	v_cndmask_b32_e64 v192, v192, v203, s[38:39]
	v_mul_f32_e32 v192, v216, v192
	v_cvt_f32_ubyte2_e32 v216, v197
	v_rcp_f32_e32 v216, v216
	v_cvt_f32_ubyte3_e32 v197, v197
	s_and_b32 s1, s30, 0x300
	v_cndmask_b32_e64 v216, v216, v203, s[38:39]
	v_mul_f32_e32 v216, v217, v216
	v_rcp_f32_e32 v217, v197
	v_cvt_f32_ubyte3_e32 v193, v193
	v_lshl_add_u64 v[194:195], s[12:13], 0, v[194:195]
	s_lshl_b32 s30, s1, 1
	v_mul_f32_e32 v197, v124, v216
	v_cndmask_b32_e64 v216, v217, v203, s[38:39]
	v_lshl_add_u64 v[194:195], v[194:195], 0, s[30:31]
	v_mul_f32_e32 v193, v193, v216
	v_cndmask_b32_e64 v216, 0, 1, s[38:39]
	v_lshl_add_u64 v[194:195], v[194:195], 0, v[0:1]
	v_mul_f32_e32 v145, v122, v145
	v_mul_f32_e32 v192, v123, v192
	v_cmp_ne_u32_e64 s[40:41], 1, v216
	s_andn2_b64 vcc, exec, s[38:39]
	v_mul_f32_e32 v193, v125, v193
	s_cbranch_vccnz .LBB0_42
	v_cvt_pk_bf16_f32 v216, v213, v214
	v_cvt_pk_bf16_f32 v217, v196, v215
	v_cvt_pk_bf16_f32 v218, v145, v192
	v_cvt_pk_bf16_f32 v219, v197, v193
	global_store_dwordx4 v[194:195], v[216:219], off
	s_branch .LBB0_43
